# EpiConv: conv edge taps fetched by the DPP operand of v_fmac (no separate row-shift moves)
# baseline (speedup 1.0000x reference)
;     __device__ __forceinline__ void operator()(const f32x4 (&acc)[2][2][4][2], const Unit& u, int wr, int wc, int fr, int fq) const {
;     ...
;             for (int m = 0; m < 4; ++m) { const int t = tbase + 16 * m + fr; const bool vin = (t >= 0) && (t < slen); const int grow = seqbase + (vin ? t : 0);
;                 const f32x4 p = *(const f32x4*)(PS + (size_t)grow * 16 + 4 * fq); float s = (p[0] + p[1]) + (p[2] + p[3]); s = bfly_add<16>(s); s = bfly_add<32>(s); rs[m] = vin ? rsqrtf(s * (1.f / DM) + EPS) : 0.f; }
;             unsigned outw[4][2][2];
; #pragma unroll
;             for (int n = 0; n < 2; ++n)
; #pragma unroll
;                 for (int jp = 0; jp < 2; ++jp) {
;                     const int cidx = (4 * n + 2 * jp) * 2;
;                     const f32x4 c0a = ct[cidx], c0b = ct[cidx + 1], c1a = ct[cidx + 2], c1b = ct[cidx + 3];
;                     const f32x2 wv0 = {c0a[0], c1a[0]}, wv1 = {c0a[1], c1a[1]}, wv2 = {c0a[2], c1a[2]}, bv = {c0a[3], c1a[3]};
;                     const f32x2 wg0 = {c0b[0], c1b[0]}, wg1 = {c0b[1], c1b[1]}, wg2 = {c0b[2], c1b[2]}, bg = {c0b[3], c1b[3]};
;                     f32x2 uv[4], ug[4], cv[4];
; #pragma unroll
;                     for (int m = 0; m < 4; ++m) { uv[m] = (f32x2){acc[ai][0][m][n][2 * jp], acc[ai][0][m][n][2 * jp + 1]}; ug[m] = (f32x2){acc[ai][1][m][n][2 * jp], acc[ai][1][m][n][2 * jp + 1]}; }
;                     asm volatile("" : "+v"(uv[0]), "+v"(uv[1]), "+v"(uv[2]), "+v"(uv[3]), "+v"(ug[0]), "+v"(ug[1]), "+v"(ug[2]), "+v"(ug[3]));
;                     {
;                         f32x2 rv[4], lv[4];
; #pragma unroll
;                         for (int m = 0; m < 4; ++m) { uv[m] = uv[m] * rs[m]; rv[m] = (f32x2){dpp_ror1(uv[m][0]), dpp_ror1(uv[m][1])}; lv[m] = (f32x2){dpp_ror15(uv[m][0]), dpp_ror15(uv[m][1])}; }
; #pragma unroll
;                         for (int m = 0; m < 4; ++m) { const f32x2 pv_ = (m > 0 && f0) ? rv[m > 0 ? m - 1 : 0] : rv[m], nv_ = (m < 3 && f15) ? lv[m < 3 ? m + 1 : 3] : lv[m];
;                             cv[m] = bv + wv0 * pv_ + wv1 * uv[m] + wv2 * nv_; }
;                     }
;                     asm volatile("" : "+v"(cv[0]), "+v"(cv[1]), "+v"(cv[2]), "+v"(cv[3]));
;                     {
;                         f32x2 rg[4], lg[4];
; #pragma unroll
.LBB0_790:
	s_lshl_b32 s92, s33, 12
	s_add_u32 s64, s100, s92
	s_addc_u32 s65, s101, 0
	s_lshl_b32 s92, s33, 8
	s_add_u32 s86, s98, s92
	s_addc_u32 s87, s99, 0
	v_mov_b32_e32 v252, s78
	s_movk_i32 s54, 0x1600
	global_load_dwordx4 v[190:193], v172, s[64:65]
	global_load_dwordx4 v[194:197], v172, s[64:65] offset:16
	global_load_dwordx4 v[198:201], v172, s[64:65] offset:32
	global_load_dwordx4 v[202:205], v172, s[64:65] offset:48
	v_lshrrev_b32_e32 v176, 4, v165
	v_add_u32_e32 v176, v176, v174
	v_cmp_gt_u32_e32 vcc, s91, v176
	s_waitcnt vmcnt(4)
	v_pk_add_f32 v[240:241], v[240:241], v[244:245]
	v_pk_add_f32 v[242:243], v[242:243], v[246:247]
	v_pk_add_f32 v[248:249], v[248:249], v[160:161]
	v_pk_add_f32 v[250:251], v[250:251], v[162:163]
	v_pk_add_f32 v[240:241], v[240:241], v[248:249]
	v_pk_add_f32 v[242:243], v[242:243], v[250:251]
	v_pk_add_f32 v[240:241], v[240:241], v[242:243]
	v_add_f32_e32 v240, v240, v241
	v_fma_f32 v240, v240, s82, v252
	v_rsq_f32_e32 v240, v240
	s_nop 0
	v_cndmask_b32_e32 v178, 0, v240, vcc
	v_mov_b32_e32 v180, v178
	s_nop 1
	v_permlane16_swap_b32_e32 v178, v180
	v_mov_b32_e32 v182, v178
	v_mov_b32_e32 v144, v180
	s_nop 1
	v_permlane32_swap_b32_e32 v178, v182
	v_permlane32_swap_b32_e32 v180, v144
	global_load_dwordx4 v[206:209], v172, s[64:65] offset:64
	global_load_dwordx4 v[210:213], v172, s[64:65] offset:80
	global_load_dwordx4 v[214:217], v172, s[64:65] offset:96
	global_load_dwordx4 v[218:221], v172, s[64:65] offset:112
	s_waitcnt vmcnt(4)
	v_pk_mul_f32 v[124:125], v[124:125], v[178:179] op_sel_hi:[1,0]
	v_pk_mul_f32 v[120:121], v[120:121], v[180:181] op_sel_hi:[1,0]
	v_pk_mul_f32 v[116:117], v[116:117], v[182:183] op_sel_hi:[1,0]
	v_pk_mul_f32 v[112:113], v[112:113], v[144:145] op_sel_hi:[1,0]
	v_pk_mul_f32 v[108:109], v[108:109], v[178:179] op_sel_hi:[1,0]
	v_pk_mul_f32 v[104:105], v[104:105], v[180:181] op_sel_hi:[1,0]
	v_pk_mul_f32 v[100:101], v[100:101], v[182:183] op_sel_hi:[1,0]
	v_pk_mul_f32 v[96:97], v[96:97], v[144:145] op_sel_hi:[1,0]
	v_pk_fma_f32 v[224:225], v[192:193], v[124:125], v[196:197]
	v_pk_fma_f32 v[226:227], v[190:191], v[124:125], v[196:197]
	v_pk_fma_f32 v[228:229], v[190:191], v[120:121], v[196:197]
	v_pk_fma_f32 v[230:231], v[190:191], v[116:117], v[196:197]
	v_pk_fma_f32 v[224:225], v[194:195], v[120:121], v[224:225]
	v_pk_fma_f32 v[226:227], v[192:193], v[120:121], v[226:227]
	v_pk_fma_f32 v[228:229], v[192:193], v[116:117], v[228:229]
	v_pk_fma_f32 v[230:231], v[192:193], v[112:113], v[230:231]
	v_pk_fma_f32 v[226:227], v[194:195], v[116:117], v[226:227]
	v_pk_fma_f32 v[228:229], v[194:195], v[112:113], v[228:229]
	v_fmac_f32_dpp v224, v112, v190 row_shr:1 row_mask:0xf bank_mask:0xf bound_ctrl:1
	v_fmac_f32_dpp v225, v113, v191 row_shr:1 row_mask:0xf bank_mask:0xf bound_ctrl:1
	v_fmac_f32_dpp v230, v124, v194 row_shl:1 row_mask:0xf bank_mask:0xf bound_ctrl:1
	v_fmac_f32_dpp v231, v125, v195 row_shl:1 row_mask:0xf bank_mask:0xf bound_ctrl:1
	v_pk_fma_f32 v[232:233], v[200:201], v[108:109], v[204:205]
	v_pk_fma_f32 v[234:235], v[198:199], v[108:109], v[204:205]
	v_pk_fma_f32 v[236:237], v[198:199], v[104:105], v[204:205]
	v_pk_fma_f32 v[238:239], v[198:199], v[100:101], v[204:205]
	v_pk_fma_f32 v[232:233], v[202:203], v[104:105], v[232:233]
	v_pk_fma_f32 v[234:235], v[200:201], v[104:105], v[234:235]
	v_pk_fma_f32 v[236:237], v[200:201], v[100:101], v[236:237]
	v_pk_fma_f32 v[238:239], v[200:201], v[96:97], v[238:239]
	v_pk_fma_f32 v[234:235], v[202:203], v[100:101], v[234:235]
	v_pk_fma_f32 v[236:237], v[202:203], v[96:97], v[236:237]
	v_fmac_f32_dpp v232, v96, v198 row_shr:1 row_mask:0xf bank_mask:0xf bound_ctrl:1
	v_fmac_f32_dpp v233, v97, v199 row_shr:1 row_mask:0xf bank_mask:0xf bound_ctrl:1
	v_fmac_f32_dpp v238, v108, v202 row_shl:1 row_mask:0xf bank_mask:0xf bound_ctrl:1
	v_fmac_f32_dpp v239, v109, v203 row_shl:1 row_mask:0xf bank_mask:0xf bound_ctrl:1
	v_exp_f32_e64 v240, -v232
	v_exp_f32_e64 v241, -v233
	v_exp_f32_e64 v242, -v234
	v_exp_f32_e64 v243, -v235
	v_exp_f32_e64 v244, -v236
	v_exp_f32_e64 v245, -v237
	v_exp_f32_e64 v246, -v238
	v_exp_f32_e64 v247, -v239
	v_pk_mul_f32 v[224:225], v[224:225], v[232:233]
	v_pk_mul_f32 v[226:227], v[226:227], v[234:235]
	v_pk_mul_f32 v[228:229], v[228:229], v[236:237]
	v_pk_mul_f32 v[230:231], v[230:231], v[238:239]
	v_pk_add_f32 v[240:241], v[240:241], 1.0 op_sel_hi:[1,0]
	v_pk_add_f32 v[242:243], v[242:243], 1.0 op_sel_hi:[1,0]
	v_pk_add_f32 v[244:245], v[244:245], 1.0 op_sel_hi:[1,0]
	v_pk_add_f32 v[246:247], v[246:247], 1.0 op_sel_hi:[1,0]
	v_rcp_f32_e32 v240, v240
	v_rcp_f32_e32 v241, v241
	v_rcp_f32_e32 v242, v242
	v_rcp_f32_e32 v243, v243
	v_rcp_f32_e32 v244, v244
	v_rcp_f32_e32 v245, v245
	v_rcp_f32_e32 v246, v246
	v_rcp_f32_e32 v247, v247
	s_nop 0
	v_pk_mul_f32 v[224:225], v[224:225], v[240:241]
	v_pk_mul_f32 v[226:227], v[226:227], v[242:243]
	v_pk_mul_f32 v[228:229], v[228:229], v[244:245]
	v_pk_mul_f32 v[230:231], v[230:231], v[246:247]
	v_cvt_pk_bf16_f32 v128, v224, v225
	v_cvt_pk_bf16_f32 v132, v226, v227
	v_cvt_pk_bf16_f32 v136, v228, v229
	v_cvt_pk_bf16_f32 v140, v230, v231
	global_load_dwordx4 v[190:193], v172, s[64:65] offset:128
	global_load_dwordx4 v[194:197], v172, s[64:65] offset:144
	global_load_dwordx4 v[198:201], v172, s[64:65] offset:160
	global_load_dwordx4 v[202:205], v172, s[64:65] offset:176
	s_waitcnt vmcnt(4)
;     __device__ __forceinline__ void operator()(const f32x4 (&acc)[2][2][4][2], const Unit& u, int wr, int wc, int fr, int fq) const {
;     ...
;                     const f32x4 c0a = ct[cidx], c0b = ct[cidx + 1], c1a = ct[cidx + 2], c1b = ct[cidx + 3];
;                     const f32x2 wv0 = {c0a[0], c1a[0]}, wv1 = {c0a[1], c1a[1]}, wv2 = {c0a[2], c1a[2]}, bv = {c0a[3], c1a[3]};
;                     const f32x2 wg0 = {c0b[0], c1b[0]}, wg1 = {c0b[1], c1b[1]}, wg2 = {c0b[2], c1b[2]}, bg = {c0b[3], c1b[3]};
;                     f32x2 uv[4], ug[4], cv[4];
; #pragma unroll
;                     for (int m = 0; m < 4; ++m) { uv[m] = (f32x2){acc[ai][0][m][n][2 * jp], acc[ai][0][m][n][2 * jp + 1]}; ug[m] = (f32x2){acc[ai][1][m][n][2 * jp], acc[ai][1][m][n][2 * jp + 1]}; }
;                     asm volatile("" : "+v"(uv[0]), "+v"(uv[1]), "+v"(uv[2]), "+v"(uv[3]), "+v"(ug[0]), "+v"(ug[1]), "+v"(ug[2]), "+v"(ug[3]));
;                     {
;                         f32x2 rv[4], lv[4];
; #pragma unroll
;                         for (int m = 0; m < 4; ++m) { uv[m] = uv[m] * rs[m]; rv[m] = (f32x2){dpp_ror1(uv[m][0]), dpp_ror1(uv[m][1])}; lv[m] = (f32x2){dpp_ror15(uv[m][0]), dpp_ror15(uv[m][1])}; }
; #pragma unroll
;                         for (int m = 0; m < 4; ++m) { const f32x2 pv_ = (m > 0 && f0) ? rv[m > 0 ? m - 1 : 0] : rv[m], nv_ = (m < 3 && f15) ? lv[m < 3 ? m + 1 : 3] : lv[m];
;                             cv[m] = bv + wv0 * pv_ + wv1 * uv[m] + wv2 * nv_; }
;                     }
;                     asm volatile("" : "+v"(cv[0]), "+v"(cv[1]), "+v"(cv[2]), "+v"(cv[3]));
;                     {
;                         f32x2 rg[4], lg[4];
; #pragma unroll
;                         for (int m = 0; m < 4; ++m) { ug[m] = ug[m] * rs[m]; rg[m] = (f32x2){dpp_ror1(ug[m][0]), dpp_ror1(ug[m][1])}; lg[m] = (f32x2){dpp_ror15(ug[m][0]), dpp_ror15(ug[m][1])}; }
; #pragma unroll
;                         for (int m = 0; m < 4; ++m) { const f32x2 pg_ = (m > 0 && f0) ? rg[m > 0 ? m - 1 : 0] : rg[m], ng_ = (m < 3 && f15) ? lg[m < 3 ? m + 1 : 3] : lg[m];
;                             const f32x2 cgt = bg + wg0 * pg_ + wg1 * ug[m] + wg2 * ng_;
;                             const f32x2 e = cgt * (-LOG2E);
;                             const f32x2 d = (f32x2){__builtin_amdgcn_exp2f(e[0]), __builtin_amdgcn_exp2f(e[1])} + 1.f;
	v_pk_mul_f32 v[126:127], v[126:127], v[178:179] op_sel_hi:[1,0]
	v_pk_mul_f32 v[122:123], v[122:123], v[180:181] op_sel_hi:[1,0]
	v_pk_mul_f32 v[118:119], v[118:119], v[182:183] op_sel_hi:[1,0]
	v_pk_mul_f32 v[114:115], v[114:115], v[144:145] op_sel_hi:[1,0]
	v_pk_mul_f32 v[110:111], v[110:111], v[178:179] op_sel_hi:[1,0]
	v_pk_mul_f32 v[106:107], v[106:107], v[180:181] op_sel_hi:[1,0]
	v_pk_mul_f32 v[102:103], v[102:103], v[182:183] op_sel_hi:[1,0]
	v_pk_mul_f32 v[98:99], v[98:99], v[144:145] op_sel_hi:[1,0]
	v_pk_fma_f32 v[224:225], v[208:209], v[126:127], v[212:213]
	v_pk_fma_f32 v[226:227], v[206:207], v[126:127], v[212:213]
	v_pk_fma_f32 v[228:229], v[206:207], v[122:123], v[212:213]
	v_pk_fma_f32 v[230:231], v[206:207], v[118:119], v[212:213]
	v_pk_fma_f32 v[224:225], v[210:211], v[122:123], v[224:225]
	v_pk_fma_f32 v[226:227], v[208:209], v[122:123], v[226:227]
	v_pk_fma_f32 v[228:229], v[208:209], v[118:119], v[228:229]
	v_pk_fma_f32 v[230:231], v[208:209], v[114:115], v[230:231]
	v_pk_fma_f32 v[226:227], v[210:211], v[118:119], v[226:227]
	v_pk_fma_f32 v[228:229], v[210:211], v[114:115], v[228:229]
	v_fmac_f32_dpp v224, v114, v206 row_shr:1 row_mask:0xf bank_mask:0xf bound_ctrl:1
	v_fmac_f32_dpp v225, v115, v207 row_shr:1 row_mask:0xf bank_mask:0xf bound_ctrl:1
	v_fmac_f32_dpp v230, v126, v210 row_shl:1 row_mask:0xf bank_mask:0xf bound_ctrl:1
	v_fmac_f32_dpp v231, v127, v211 row_shl:1 row_mask:0xf bank_mask:0xf bound_ctrl:1
	v_pk_fma_f32 v[232:233], v[216:217], v[110:111], v[220:221]
	v_pk_fma_f32 v[234:235], v[214:215], v[110:111], v[220:221]
	v_pk_fma_f32 v[236:237], v[214:215], v[106:107], v[220:221]
	v_pk_fma_f32 v[238:239], v[214:215], v[102:103], v[220:221]
	v_pk_fma_f32 v[232:233], v[218:219], v[106:107], v[232:233]
	v_pk_fma_f32 v[234:235], v[216:217], v[106:107], v[234:235]
	v_pk_fma_f32 v[236:237], v[216:217], v[102:103], v[236:237]
	v_pk_fma_f32 v[238:239], v[216:217], v[98:99], v[238:239]
	v_pk_fma_f32 v[234:235], v[218:219], v[102:103], v[234:235]
	v_pk_fma_f32 v[236:237], v[218:219], v[98:99], v[236:237]
	v_fmac_f32_dpp v232, v98, v214 row_shr:1 row_mask:0xf bank_mask:0xf bound_ctrl:1
	v_fmac_f32_dpp v233, v99, v215 row_shr:1 row_mask:0xf bank_mask:0xf bound_ctrl:1
	v_fmac_f32_dpp v238, v110, v218 row_shl:1 row_mask:0xf bank_mask:0xf bound_ctrl:1
	v_fmac_f32_dpp v239, v111, v219 row_shl:1 row_mask:0xf bank_mask:0xf bound_ctrl:1
	v_exp_f32_e64 v240, -v232
	v_exp_f32_e64 v241, -v233
	v_exp_f32_e64 v242, -v234
	v_exp_f32_e64 v243, -v235
	v_exp_f32_e64 v244, -v236
	v_exp_f32_e64 v245, -v237
	v_exp_f32_e64 v246, -v238
	v_exp_f32_e64 v247, -v239
	v_pk_mul_f32 v[224:225], v[224:225], v[232:233]
	v_pk_mul_f32 v[226:227], v[226:227], v[234:235]
	v_pk_mul_f32 v[228:229], v[228:229], v[236:237]
	v_pk_mul_f32 v[230:231], v[230:231], v[238:239]
	v_pk_add_f32 v[240:241], v[240:241], 1.0 op_sel_hi:[1,0]
	v_pk_add_f32 v[242:243], v[242:243], 1.0 op_sel_hi:[1,0]
	v_pk_add_f32 v[244:245], v[244:245], 1.0 op_sel_hi:[1,0]
	v_pk_add_f32 v[246:247], v[246:247], 1.0 op_sel_hi:[1,0]
	v_rcp_f32_e32 v240, v240
	v_rcp_f32_e32 v241, v241
	v_rcp_f32_e32 v242, v242
	v_rcp_f32_e32 v243, v243
	v_rcp_f32_e32 v244, v244
	v_rcp_f32_e32 v245, v245
	v_rcp_f32_e32 v246, v246
	v_rcp_f32_e32 v247, v247
	s_nop 0
	v_pk_mul_f32 v[224:225], v[224:225], v[240:241]
	v_pk_mul_f32 v[226:227], v[226:227], v[242:243]
	v_pk_mul_f32 v[228:229], v[228:229], v[244:245]
	v_pk_mul_f32 v[230:231], v[230:231], v[246:247]
	v_cvt_pk_bf16_f32 v129, v224, v225
	v_cvt_pk_bf16_f32 v133, v226, v227
	v_cvt_pk_bf16_f32 v137, v228, v229
	v_cvt_pk_bf16_f32 v141, v230, v231
	global_load_dwordx4 v[206:209], v172, s[64:65] offset:192
	global_load_dwordx4 v[210:213], v172, s[64:65] offset:208
	global_load_dwordx4 v[214:217], v172, s[64:65] offset:224
	global_load_dwordx4 v[218:221], v172, s[64:65] offset:240
	s_waitcnt vmcnt(4)
	v_pk_mul_f32 v[92:93], v[92:93], v[178:179] op_sel_hi:[1,0]
	v_pk_mul_f32 v[88:89], v[88:89], v[180:181] op_sel_hi:[1,0]
	v_pk_mul_f32 v[84:85], v[84:85], v[182:183] op_sel_hi:[1,0]
	v_pk_mul_f32 v[80:81], v[80:81], v[144:145] op_sel_hi:[1,0]
	v_pk_mul_f32 v[76:77], v[76:77], v[178:179] op_sel_hi:[1,0]
	v_pk_mul_f32 v[72:73], v[72:73], v[180:181] op_sel_hi:[1,0]
	v_pk_mul_f32 v[68:69], v[68:69], v[182:183] op_sel_hi:[1,0]
	v_pk_mul_f32 v[64:65], v[64:65], v[144:145] op_sel_hi:[1,0]
	v_pk_fma_f32 v[224:225], v[192:193], v[92:93], v[196:197]
	v_pk_fma_f32 v[226:227], v[190:191], v[92:93], v[196:197]
	v_pk_fma_f32 v[228:229], v[190:191], v[88:89], v[196:197]
	v_pk_fma_f32 v[230:231], v[190:191], v[84:85], v[196:197]
	v_pk_fma_f32 v[224:225], v[194:195], v[88:89], v[224:225]
	v_pk_fma_f32 v[226:227], v[192:193], v[88:89], v[226:227]
	v_pk_fma_f32 v[228:229], v[192:193], v[84:85], v[228:229]
	v_pk_fma_f32 v[230:231], v[192:193], v[80:81], v[230:231]
	v_pk_fma_f32 v[226:227], v[194:195], v[84:85], v[226:227]
	v_pk_fma_f32 v[228:229], v[194:195], v[80:81], v[228:229]
	v_fmac_f32_dpp v224, v80, v190 row_shr:1 row_mask:0xf bank_mask:0xf bound_ctrl:1
	v_fmac_f32_dpp v225, v81, v191 row_shr:1 row_mask:0xf bank_mask:0xf bound_ctrl:1
	v_fmac_f32_dpp v230, v92, v194 row_shl:1 row_mask:0xf bank_mask:0xf bound_ctrl:1
	v_fmac_f32_dpp v231, v93, v195 row_shl:1 row_mask:0xf bank_mask:0xf bound_ctrl:1
	v_pk_fma_f32 v[232:233], v[200:201], v[76:77], v[204:205]
	v_pk_fma_f32 v[234:235], v[198:199], v[76:77], v[204:205]
	v_pk_fma_f32 v[236:237], v[198:199], v[72:73], v[204:205]
	v_pk_fma_f32 v[238:239], v[198:199], v[68:69], v[204:205]
	v_pk_fma_f32 v[232:233], v[202:203], v[72:73], v[232:233]
	v_pk_fma_f32 v[234:235], v[200:201], v[72:73], v[234:235]
;     __device__ __forceinline__ void operator()(const f32x4 (&acc)[2][2][4][2], const Unit& u, int wr, int wc, int fr, int fq) const {
;     ...
;             for (int m = 0; m < 4; ++m) { const int t = tbase + 16 * m + fr; const bool vin = (t >= 0) && (t < slen); const int grow = seqbase + (vin ? t : 0);
;                 const f32x4 p = *(const f32x4*)(PS + (size_t)grow * 16 + 4 * fq); float s = (p[0] + p[1]) + (p[2] + p[3]); s = bfly_add<16>(s); s = bfly_add<32>(s); rs[m] = vin ? rsqrtf(s * (1.f / DM) + EPS) : 0.f; }
;             unsigned outw[4][2][2];
; #pragma unroll
;             for (int n = 0; n < 2; ++n)
; #pragma unroll
;                 for (int jp = 0; jp < 2; ++jp) {
;                     const int cidx = (4 * n + 2 * jp) * 2;
;                     const f32x4 c0a = ct[cidx], c0b = ct[cidx + 1], c1a = ct[cidx + 2], c1b = ct[cidx + 3];
;                     const f32x2 wv0 = {c0a[0], c1a[0]}, wv1 = {c0a[1], c1a[1]}, wv2 = {c0a[2], c1a[2]}, bv = {c0a[3], c1a[3]};
;                     const f32x2 wg0 = {c0b[0], c1b[0]}, wg1 = {c0b[1], c1b[1]}, wg2 = {c0b[2], c1b[2]}, bg = {c0b[3], c1b[3]};
;                     f32x2 uv[4], ug[4], cv[4];
; #pragma unroll
;                     for (int m = 0; m < 4; ++m) { uv[m] = (f32x2){acc[ai][0][m][n][2 * jp], acc[ai][0][m][n][2 * jp + 1]}; ug[m] = (f32x2){acc[ai][1][m][n][2 * jp], acc[ai][1][m][n][2 * jp + 1]}; }
;                     asm volatile("" : "+v"(uv[0]), "+v"(uv[1]), "+v"(uv[2]), "+v"(uv[3]), "+v"(ug[0]), "+v"(ug[1]), "+v"(ug[2]), "+v"(ug[3]));
;                     {
;                         f32x2 rv[4], lv[4];
; #pragma unroll
;                         for (int m = 0; m < 4; ++m) { uv[m] = uv[m] * rs[m]; rv[m] = (f32x2){dpp_ror1(uv[m][0]), dpp_ror1(uv[m][1])}; lv[m] = (f32x2){dpp_ror15(uv[m][0]), dpp_ror15(uv[m][1])}; }
; #pragma unroll
;                         for (int m = 0; m < 4; ++m) { const f32x2 pv_ = (m > 0 && f0) ? rv[m > 0 ? m - 1 : 0] : rv[m], nv_ = (m < 3 && f15) ? lv[m < 3 ? m + 1 : 3] : lv[m];
;                             cv[m] = bv + wv0 * pv_ + wv1 * uv[m] + wv2 * nv_; }
;                     }
;                     asm volatile("" : "+v"(cv[0]), "+v"(cv[1]), "+v"(cv[2]), "+v"(cv[3]));
;                     {
;                         f32x2 rg[4], lg[4];
; #pragma unroll
	v_pk_fma_f32 v[236:237], v[200:201], v[68:69], v[236:237]
	v_pk_fma_f32 v[238:239], v[200:201], v[64:65], v[238:239]
	v_pk_fma_f32 v[234:235], v[202:203], v[68:69], v[234:235]
	v_pk_fma_f32 v[236:237], v[202:203], v[64:65], v[236:237]
	v_fmac_f32_dpp v232, v64, v198 row_shr:1 row_mask:0xf bank_mask:0xf bound_ctrl:1
	v_fmac_f32_dpp v233, v65, v199 row_shr:1 row_mask:0xf bank_mask:0xf bound_ctrl:1
	v_fmac_f32_dpp v238, v76, v202 row_shl:1 row_mask:0xf bank_mask:0xf bound_ctrl:1
	v_fmac_f32_dpp v239, v77, v203 row_shl:1 row_mask:0xf bank_mask:0xf bound_ctrl:1
	v_exp_f32_e64 v240, -v232
	v_exp_f32_e64 v241, -v233
	v_exp_f32_e64 v242, -v234
	v_exp_f32_e64 v243, -v235
	v_exp_f32_e64 v244, -v236
	v_exp_f32_e64 v245, -v237
	v_exp_f32_e64 v246, -v238
	v_exp_f32_e64 v247, -v239
	v_pk_mul_f32 v[224:225], v[224:225], v[232:233]
	v_pk_mul_f32 v[226:227], v[226:227], v[234:235]
	v_pk_mul_f32 v[228:229], v[228:229], v[236:237]
	v_pk_mul_f32 v[230:231], v[230:231], v[238:239]
	v_pk_add_f32 v[240:241], v[240:241], 1.0 op_sel_hi:[1,0]
	v_pk_add_f32 v[242:243], v[242:243], 1.0 op_sel_hi:[1,0]
	v_pk_add_f32 v[244:245], v[244:245], 1.0 op_sel_hi:[1,0]
	v_pk_add_f32 v[246:247], v[246:247], 1.0 op_sel_hi:[1,0]
	v_rcp_f32_e32 v240, v240
	v_rcp_f32_e32 v241, v241
	v_rcp_f32_e32 v242, v242
	v_rcp_f32_e32 v243, v243
	v_rcp_f32_e32 v244, v244
	v_rcp_f32_e32 v245, v245
	v_rcp_f32_e32 v246, v246
	v_rcp_f32_e32 v247, v247
	s_nop 0
	v_pk_mul_f32 v[224:225], v[224:225], v[240:241]
	v_pk_mul_f32 v[226:227], v[226:227], v[242:243]
	v_pk_mul_f32 v[228:229], v[228:229], v[244:245]
	v_pk_mul_f32 v[230:231], v[230:231], v[246:247]
	v_cvt_pk_bf16_f32 v130, v224, v225
	v_cvt_pk_bf16_f32 v134, v226, v227
	v_cvt_pk_bf16_f32 v138, v228, v229
	v_cvt_pk_bf16_f32 v142, v230, v231
	s_waitcnt vmcnt(0)
	v_add_u32_e32 v253, 0x7c, v174
	v_lshrrev_b32_e32 v176, 4, v165
	v_add_u32_e32 v176, v176, v253
	v_cmp_gt_u32_e32 vcc, s91, v176
	s_nop 1
	v_cndmask_b32_e32 v176, 0, v176, vcc
	v_add_u32_e32 v176, s88, v176
	v_lshlrev_b32_e32 v248, 6, v176
	global_load_dwordx4 v[190:193], v248, s[70:71]
	global_load_dwordx4 v[194:197], v248, s[70:71] offset:16
	global_load_dwordx4 v[198:201], v248, s[70:71] offset:32
	global_load_dwordx4 v[202:205], v248, s[70:71] offset:48
	v_pk_mul_f32 v[94:95], v[94:95], v[178:179] op_sel_hi:[1,0]
	v_pk_mul_f32 v[90:91], v[90:91], v[180:181] op_sel_hi:[1,0]
	v_pk_mul_f32 v[86:87], v[86:87], v[182:183] op_sel_hi:[1,0]
	v_pk_mul_f32 v[82:83], v[82:83], v[144:145] op_sel_hi:[1,0]
	v_pk_mul_f32 v[78:79], v[78:79], v[178:179] op_sel_hi:[1,0]
	v_pk_mul_f32 v[74:75], v[74:75], v[180:181] op_sel_hi:[1,0]
	v_pk_mul_f32 v[70:71], v[70:71], v[182:183] op_sel_hi:[1,0]
	v_pk_mul_f32 v[66:67], v[66:67], v[144:145] op_sel_hi:[1,0]
	v_pk_fma_f32 v[224:225], v[208:209], v[94:95], v[212:213]
	v_pk_fma_f32 v[226:227], v[206:207], v[94:95], v[212:213]
	v_pk_fma_f32 v[228:229], v[206:207], v[90:91], v[212:213]
	v_pk_fma_f32 v[230:231], v[206:207], v[86:87], v[212:213]
	v_pk_fma_f32 v[224:225], v[210:211], v[90:91], v[224:225]
	v_pk_fma_f32 v[226:227], v[208:209], v[90:91], v[226:227]
	v_pk_fma_f32 v[228:229], v[208:209], v[86:87], v[228:229]
	v_pk_fma_f32 v[230:231], v[208:209], v[82:83], v[230:231]
	v_pk_fma_f32 v[226:227], v[210:211], v[86:87], v[226:227]
	v_pk_fma_f32 v[228:229], v[210:211], v[82:83], v[228:229]
	v_fmac_f32_dpp v224, v82, v206 row_shr:1 row_mask:0xf bank_mask:0xf bound_ctrl:1
	v_fmac_f32_dpp v225, v83, v207 row_shr:1 row_mask:0xf bank_mask:0xf bound_ctrl:1
	v_fmac_f32_dpp v230, v94, v210 row_shl:1 row_mask:0xf bank_mask:0xf bound_ctrl:1
	v_fmac_f32_dpp v231, v95, v211 row_shl:1 row_mask:0xf bank_mask:0xf bound_ctrl:1
	v_pk_fma_f32 v[232:233], v[216:217], v[78:79], v[220:221]
	v_pk_fma_f32 v[234:235], v[214:215], v[78:79], v[220:221]
	v_pk_fma_f32 v[236:237], v[214:215], v[74:75], v[220:221]
	v_pk_fma_f32 v[238:239], v[214:215], v[70:71], v[220:221]
	v_pk_fma_f32 v[232:233], v[218:219], v[74:75], v[232:233]
	v_pk_fma_f32 v[234:235], v[216:217], v[74:75], v[234:235]
	v_pk_fma_f32 v[236:237], v[216:217], v[70:71], v[236:237]
	v_pk_fma_f32 v[238:239], v[216:217], v[66:67], v[238:239]
	v_pk_fma_f32 v[234:235], v[218:219], v[70:71], v[234:235]
	v_pk_fma_f32 v[236:237], v[218:219], v[66:67], v[236:237]
	v_fmac_f32_dpp v232, v66, v214 row_shr:1 row_mask:0xf bank_mask:0xf bound_ctrl:1
	v_fmac_f32_dpp v233, v67, v215 row_shr:1 row_mask:0xf bank_mask:0xf bound_ctrl:1
	v_fmac_f32_dpp v238, v78, v218 row_shl:1 row_mask:0xf bank_mask:0xf bound_ctrl:1
	v_fmac_f32_dpp v239, v79, v219 row_shl:1 row_mask:0xf bank_mask:0xf bound_ctrl:1
	v_exp_f32_e64 v240, -v232
	v_exp_f32_e64 v241, -v233
	v_exp_f32_e64 v242, -v234
	v_exp_f32_e64 v243, -v235
	v_exp_f32_e64 v244, -v236
	v_exp_f32_e64 v245, -v237
	v_exp_f32_e64 v246, -v238
	v_exp_f32_e64 v247, -v239
	v_pk_mul_f32 v[224:225], v[224:225], v[232:233]
	v_pk_mul_f32 v[226:227], v[226:227], v[234:235]
	v_pk_mul_f32 v[228:229], v[228:229], v[236:237]
	v_pk_mul_f32 v[230:231], v[230:231], v[238:239]
	v_pk_add_f32 v[240:241], v[240:241], 1.0 op_sel_hi:[1,0]
	v_pk_add_f32 v[242:243], v[242:243], 1.0 op_sel_hi:[1,0]
	v_pk_add_f32 v[244:245], v[244:245], 1.0 op_sel_hi:[1,0]
	v_pk_add_f32 v[246:247], v[246:247], 1.0 op_sel_hi:[1,0]
	v_rcp_f32_e32 v240, v240
	v_rcp_f32_e32 v241, v241
	v_rcp_f32_e32 v242, v242
	v_rcp_f32_e32 v243, v243
	v_rcp_f32_e32 v244, v244
	v_rcp_f32_e32 v245, v245
	v_rcp_f32_e32 v246, v246
	v_rcp_f32_e32 v247, v247
	s_nop 0
	v_pk_mul_f32 v[224:225], v[224:225], v[240:241]
	v_pk_mul_f32 v[226:227], v[226:227], v[242:243]
	v_pk_mul_f32 v[228:229], v[228:229], v[244:245]
	v_pk_mul_f32 v[230:231], v[230:231], v[246:247]
;     __device__ __forceinline__ void operator()(const f32x4 (&acc)[2][2][4][2], const Unit& u, int wr, int wc, int fr, int fq) const {
;     ...
;             for (int m = 0; m < 4; ++m) { const int t = tbase + 16 * m + fr; const bool vin = (t >= 0) && (t < slen); const int grow = seqbase + (vin ? t : 0);
;                 const f32x4 p = *(const f32x4*)(PS + (size_t)grow * 16 + 4 * fq); float s = (p[0] + p[1]) + (p[2] + p[3]); s = bfly_add<16>(s); s = bfly_add<32>(s); rs[m] = vin ? rsqrtf(s * (1.f / DM) + EPS) : 0.f; }
;             unsigned outw[4][2][2];
; #pragma unroll
;             for (int n = 0; n < 2; ++n)
; #pragma unroll
;                 for (int jp = 0; jp < 2; ++jp) {
;                     const int cidx = (4 * n + 2 * jp) * 2;
;                     const f32x4 c0a = ct[cidx], c0b = ct[cidx + 1], c1a = ct[cidx + 2], c1b = ct[cidx + 3];
;                     const f32x2 wv0 = {c0a[0], c1a[0]}, wv1 = {c0a[1], c1a[1]}, wv2 = {c0a[2], c1a[2]}, bv = {c0a[3], c1a[3]};
;                     const f32x2 wg0 = {c0b[0], c1b[0]}, wg1 = {c0b[1], c1b[1]}, wg2 = {c0b[2], c1b[2]}, bg = {c0b[3], c1b[3]};
;                     f32x2 uv[4], ug[4], cv[4];
; #pragma unroll
;                     for (int m = 0; m < 4; ++m) { uv[m] = (f32x2){acc[ai][0][m][n][2 * jp], acc[ai][0][m][n][2 * jp + 1]}; ug[m] = (f32x2){acc[ai][1][m][n][2 * jp], acc[ai][1][m][n][2 * jp + 1]}; }
;                     asm volatile("" : "+v"(uv[0]), "+v"(uv[1]), "+v"(uv[2]), "+v"(uv[3]), "+v"(ug[0]), "+v"(ug[1]), "+v"(ug[2]), "+v"(ug[3]));
;                     {
;                         f32x2 rv[4], lv[4];
; #pragma unroll
;                         for (int m = 0; m < 4; ++m) { uv[m] = uv[m] * rs[m]; rv[m] = (f32x2){dpp_ror1(uv[m][0]), dpp_ror1(uv[m][1])}; lv[m] = (f32x2){dpp_ror15(uv[m][0]), dpp_ror15(uv[m][1])}; }
; #pragma unroll
;                         for (int m = 0; m < 4; ++m) { const f32x2 pv_ = (m > 0 && f0) ? rv[m > 0 ? m - 1 : 0] : rv[m], nv_ = (m < 3 && f15) ? lv[m < 3 ? m + 1 : 3] : lv[m];
;                             cv[m] = bv + wv0 * pv_ + wv1 * uv[m] + wv2 * nv_; }
;                     }
;                     asm volatile("" : "+v"(cv[0]), "+v"(cv[1]), "+v"(cv[2]), "+v"(cv[3]));
;                     {
;                         f32x2 rg[4], lg[4];
; #pragma unroll
	v_cvt_pk_bf16_f32 v131, v224, v225
	v_cvt_pk_bf16_f32 v135, v226, v227
	v_cvt_pk_bf16_f32 v139, v228, v229
	v_cvt_pk_bf16_f32 v143, v230, v231
	s_sub_i32 s51, s91, s89
	s_sub_i32 s66, s51, 4
	s_max_i32 s66, s66, 0
	v_add_u32_e32 v176, -4, v164
	v_cmp_gt_u32_e32 vcc, s66, v176
	v_add_u32_e32 v176, 0, v174
	v_add_u32_e32 v176, s88, v176
	v_mad_u32_u24 v248, v176, s54, v165
	s_mov_b64 exec, vcc
	global_store_dwordx4 v248, v[128:131], s[86:87]
	s_mov_b64 exec, -1
	s_sub_i32 s66, s51, 1
	s_max_i32 s66, s66, 0
	v_cmp_gt_u32_e32 vcc, s66, v164
	v_add_u32_e32 v176, 1, v174
	v_add_u32_e32 v176, s88, v176
	v_mad_u32_u24 v249, v176, s54, v165
	s_mov_b64 exec, vcc
	global_store_dwordx4 v249, v[132:135], s[86:87]
	s_mov_b64 exec, -1
	s_sub_i32 s66, s51, 2
	s_max_i32 s66, s66, 0
	v_cmp_gt_u32_e32 vcc, s66, v164
	v_add_u32_e32 v176, 2, v174
	v_add_u32_e32 v176, s88, v176
	v_mad_u32_u24 v250, v176, s54, v165
	s_mov_b64 exec, vcc
	global_store_dwordx4 v250, v[136:139], s[86:87]
	s_mov_b64 exec, -1
	s_sub_i32 s66, s51, 3
	s_min_i32 s66, s66, 60
	s_max_i32 s66, s66, 0
	v_cmp_gt_u32_e32 vcc, s66, v164
	v_add_u32_e32 v176, 3, v174
	v_add_u32_e32 v176, s88, v176
	v_mad_u32_u24 v251, v176, s54, v165
	s_mov_b64 exec, vcc
	global_store_dwordx4 v251, v[140:143], s[86:87]
	s_mov_b64 exec, -1
	s_addk_i32 s89, 0x7c
	v_mov_b32_e32 v174, v253
	global_load_dwordx4 v[206:209], v172, s[64:65]
	global_load_dwordx4 v[210:213], v172, s[64:65] offset:16
	global_load_dwordx4 v[214:217], v172, s[64:65] offset:32
	global_load_dwordx4 v[218:221], v172, s[64:65] offset:48
	v_lshrrev_b32_e32 v176, 4, v165
	v_add_u32_e32 v176, v176, v174
	v_cmp_gt_u32_e32 vcc, s91, v176
	s_waitcnt vmcnt(8)
	v_pk_add_f32 v[190:191], v[190:191], v[194:195]
	v_pk_add_f32 v[192:193], v[192:193], v[196:197]
	v_pk_add_f32 v[198:199], v[198:199], v[202:203]
	v_pk_add_f32 v[200:201], v[200:201], v[204:205]
	v_pk_add_f32 v[190:191], v[190:191], v[198:199]
	v_pk_add_f32 v[192:193], v[192:193], v[200:201]
	v_pk_add_f32 v[190:191], v[190:191], v[192:193]
	v_add_f32_e32 v190, v190, v191
	v_fma_f32 v190, v190, s82, v252
	v_rsq_f32_e32 v190, v190
	s_nop 0
	v_cndmask_b32_e32 v178, 0, v190, vcc
	v_mov_b32_e32 v180, v178
	s_nop 1
	v_permlane16_swap_b32_e32 v178, v180
	v_mov_b32_e32 v182, v178
	v_mov_b32_e32 v144, v180
	s_nop 1
	v_permlane32_swap_b32_e32 v178, v182
	v_permlane32_swap_b32_e32 v180, v144
	global_load_dwordx4 v[190:193], v172, s[64:65] offset:64
	global_load_dwordx4 v[194:197], v172, s[64:65] offset:80
	global_load_dwordx4 v[198:201], v172, s[64:65] offset:96
	global_load_dwordx4 v[202:205], v172, s[64:65] offset:112
	s_waitcnt vmcnt(4)
	v_pk_mul_f32 v[60:61], v[60:61], v[178:179] op_sel_hi:[1,0]
	v_pk_mul_f32 v[56:57], v[56:57], v[180:181] op_sel_hi:[1,0]
	v_pk_mul_f32 v[52:53], v[52:53], v[182:183] op_sel_hi:[1,0]
	v_pk_mul_f32 v[48:49], v[48:49], v[144:145] op_sel_hi:[1,0]
	v_pk_mul_f32 v[44:45], v[44:45], v[178:179] op_sel_hi:[1,0]
	v_pk_mul_f32 v[40:41], v[40:41], v[180:181] op_sel_hi:[1,0]
	v_pk_mul_f32 v[36:37], v[36:37], v[182:183] op_sel_hi:[1,0]
	v_pk_mul_f32 v[32:33], v[32:33], v[144:145] op_sel_hi:[1,0]
	v_pk_fma_f32 v[224:225], v[208:209], v[60:61], v[212:213]
	v_pk_fma_f32 v[226:227], v[206:207], v[60:61], v[212:213]
	v_pk_fma_f32 v[228:229], v[206:207], v[56:57], v[212:213]
	v_pk_fma_f32 v[230:231], v[206:207], v[52:53], v[212:213]
	v_pk_fma_f32 v[224:225], v[210:211], v[56:57], v[224:225]
	v_pk_fma_f32 v[226:227], v[208:209], v[56:57], v[226:227]
	v_pk_fma_f32 v[228:229], v[208:209], v[52:53], v[228:229]
	v_pk_fma_f32 v[230:231], v[208:209], v[48:49], v[230:231]
	v_pk_fma_f32 v[226:227], v[210:211], v[52:53], v[226:227]
	v_pk_fma_f32 v[228:229], v[210:211], v[48:49], v[228:229]
	v_fmac_f32_dpp v224, v48, v206 row_shr:1 row_mask:0xf bank_mask:0xf bound_ctrl:1
	v_fmac_f32_dpp v225, v49, v207 row_shr:1 row_mask:0xf bank_mask:0xf bound_ctrl:1
	v_fmac_f32_dpp v230, v60, v210 row_shl:1 row_mask:0xf bank_mask:0xf bound_ctrl:1
	v_fmac_f32_dpp v231, v61, v211 row_shl:1 row_mask:0xf bank_mask:0xf bound_ctrl:1
	v_pk_fma_f32 v[232:233], v[216:217], v[44:45], v[220:221]
	v_pk_fma_f32 v[234:235], v[214:215], v[44:45], v[220:221]
	v_pk_fma_f32 v[236:237], v[214:215], v[40:41], v[220:221]
	v_pk_fma_f32 v[238:239], v[214:215], v[36:37], v[220:221]
	v_pk_fma_f32 v[232:233], v[218:219], v[40:41], v[232:233]
	v_pk_fma_f32 v[234:235], v[216:217], v[40:41], v[234:235]
	v_pk_fma_f32 v[236:237], v[216:217], v[36:37], v[236:237]
	v_pk_fma_f32 v[238:239], v[216:217], v[32:33], v[238:239]
	v_pk_fma_f32 v[234:235], v[218:219], v[36:37], v[234:235]
	v_pk_fma_f32 v[236:237], v[218:219], v[32:33], v[236:237]
	v_fmac_f32_dpp v232, v32, v214 row_shr:1 row_mask:0xf bank_mask:0xf bound_ctrl:1
	v_fmac_f32_dpp v233, v33, v215 row_shr:1 row_mask:0xf bank_mask:0xf bound_ctrl:1
	v_fmac_f32_dpp v238, v44, v218 row_shl:1 row_mask:0xf bank_mask:0xf bound_ctrl:1
	v_fmac_f32_dpp v239, v45, v219 row_shl:1 row_mask:0xf bank_mask:0xf bound_ctrl:1
	v_exp_f32_e64 v240, -v232
	v_exp_f32_e64 v241, -v233
	v_exp_f32_e64 v242, -v234
	v_exp_f32_e64 v243, -v235
	v_exp_f32_e64 v244, -v236
	v_exp_f32_e64 v245, -v237
	v_exp_f32_e64 v246, -v238
	v_exp_f32_e64 v247, -v239
	v_pk_mul_f32 v[224:225], v[224:225], v[232:233]
	v_pk_mul_f32 v[226:227], v[226:227], v[234:235]
	v_pk_mul_f32 v[228:229], v[228:229], v[236:237]
	v_pk_mul_f32 v[230:231], v[230:231], v[238:239]
	v_pk_add_f32 v[240:241], v[240:241], 1.0 op_sel_hi:[1,0]
	v_pk_add_f32 v[242:243], v[242:243], 1.0 op_sel_hi:[1,0]
	v_pk_add_f32 v[244:245], v[244:245], 1.0 op_sel_hi:[1,0]
	v_pk_add_f32 v[246:247], v[246:247], 1.0 op_sel_hi:[1,0]
	v_rcp_f32_e32 v240, v240
	v_rcp_f32_e32 v241, v241
	v_rcp_f32_e32 v242, v242
	v_rcp_f32_e32 v243, v243
	v_rcp_f32_e32 v244, v244
	v_rcp_f32_e32 v245, v245
	v_rcp_f32_e32 v246, v246
	v_rcp_f32_e32 v247, v247
	s_nop 0
	v_pk_mul_f32 v[224:225], v[224:225], v[240:241]
	v_pk_mul_f32 v[226:227], v[226:227], v[242:243]
	v_pk_mul_f32 v[228:229], v[228:229], v[244:245]
	v_pk_mul_f32 v[230:231], v[230:231], v[246:247]
	v_cvt_pk_bf16_f32 v128, v224, v225
	v_cvt_pk_bf16_f32 v132, v226, v227
	v_cvt_pk_bf16_f32 v136, v228, v229
	v_cvt_pk_bf16_f32 v140, v230, v231
	global_load_dwordx4 v[206:209], v172, s[64:65] offset:128
	global_load_dwordx4 v[210:213], v172, s[64:65] offset:144
	global_load_dwordx4 v[214:217], v172, s[64:65] offset:160
	global_load_dwordx4 v[218:221], v172, s[64:65] offset:176
	s_waitcnt vmcnt(4)
;     __device__ __forceinline__ void operator()(const f32x4 (&acc)[2][2][4][2], const Unit& u, int wr, int wc, int fr, int fq) const {
;     ...
;                     const f32x4 c0a = ct[cidx], c0b = ct[cidx + 1], c1a = ct[cidx + 2], c1b = ct[cidx + 3];
;                     const f32x2 wv0 = {c0a[0], c1a[0]}, wv1 = {c0a[1], c1a[1]}, wv2 = {c0a[2], c1a[2]}, bv = {c0a[3], c1a[3]};
;                     const f32x2 wg0 = {c0b[0], c1b[0]}, wg1 = {c0b[1], c1b[1]}, wg2 = {c0b[2], c1b[2]}, bg = {c0b[3], c1b[3]};
;                     f32x2 uv[4], ug[4], cv[4];
; #pragma unroll
;                     for (int m = 0; m < 4; ++m) { uv[m] = (f32x2){acc[ai][0][m][n][2 * jp], acc[ai][0][m][n][2 * jp + 1]}; ug[m] = (f32x2){acc[ai][1][m][n][2 * jp], acc[ai][1][m][n][2 * jp + 1]}; }
;                     asm volatile("" : "+v"(uv[0]), "+v"(uv[1]), "+v"(uv[2]), "+v"(uv[3]), "+v"(ug[0]), "+v"(ug[1]), "+v"(ug[2]), "+v"(ug[3]));
;                     {
;                         f32x2 rv[4], lv[4];
; #pragma unroll
;                         for (int m = 0; m < 4; ++m) { uv[m] = uv[m] * rs[m]; rv[m] = (f32x2){dpp_ror1(uv[m][0]), dpp_ror1(uv[m][1])}; lv[m] = (f32x2){dpp_ror15(uv[m][0]), dpp_ror15(uv[m][1])}; }
; #pragma unroll
;                         for (int m = 0; m < 4; ++m) { const f32x2 pv_ = (m > 0 && f0) ? rv[m > 0 ? m - 1 : 0] : rv[m], nv_ = (m < 3 && f15) ? lv[m < 3 ? m + 1 : 3] : lv[m];
;                             cv[m] = bv + wv0 * pv_ + wv1 * uv[m] + wv2 * nv_; }
;                     }
;                     asm volatile("" : "+v"(cv[0]), "+v"(cv[1]), "+v"(cv[2]), "+v"(cv[3]));
;                     {
;                         f32x2 rg[4], lg[4];
; #pragma unroll
;                         for (int m = 0; m < 4; ++m) { ug[m] = ug[m] * rs[m]; rg[m] = (f32x2){dpp_ror1(ug[m][0]), dpp_ror1(ug[m][1])}; lg[m] = (f32x2){dpp_ror15(ug[m][0]), dpp_ror15(ug[m][1])}; }
; #pragma unroll
;                         for (int m = 0; m < 4; ++m) { const f32x2 pg_ = (m > 0 && f0) ? rg[m > 0 ? m - 1 : 0] : rg[m], ng_ = (m < 3 && f15) ? lg[m < 3 ? m + 1 : 3] : lg[m];
;                             const f32x2 cgt = bg + wg0 * pg_ + wg1 * ug[m] + wg2 * ng_;
;                             const f32x2 e = cgt * (-LOG2E);
;                             const f32x2 d = (f32x2){__builtin_amdgcn_exp2f(e[0]), __builtin_amdgcn_exp2f(e[1])} + 1.f;
	v_pk_mul_f32 v[62:63], v[62:63], v[178:179] op_sel_hi:[1,0]
	v_pk_mul_f32 v[58:59], v[58:59], v[180:181] op_sel_hi:[1,0]
	v_pk_mul_f32 v[54:55], v[54:55], v[182:183] op_sel_hi:[1,0]
	v_pk_mul_f32 v[50:51], v[50:51], v[144:145] op_sel_hi:[1,0]
	v_pk_mul_f32 v[46:47], v[46:47], v[178:179] op_sel_hi:[1,0]
	v_pk_mul_f32 v[42:43], v[42:43], v[180:181] op_sel_hi:[1,0]
	v_pk_mul_f32 v[38:39], v[38:39], v[182:183] op_sel_hi:[1,0]
	v_pk_mul_f32 v[34:35], v[34:35], v[144:145] op_sel_hi:[1,0]
	v_pk_fma_f32 v[224:225], v[192:193], v[62:63], v[196:197]
	v_pk_fma_f32 v[226:227], v[190:191], v[62:63], v[196:197]
	v_pk_fma_f32 v[228:229], v[190:191], v[58:59], v[196:197]
	v_pk_fma_f32 v[230:231], v[190:191], v[54:55], v[196:197]
	v_pk_fma_f32 v[224:225], v[194:195], v[58:59], v[224:225]
	v_pk_fma_f32 v[226:227], v[192:193], v[58:59], v[226:227]
	v_pk_fma_f32 v[228:229], v[192:193], v[54:55], v[228:229]
	v_pk_fma_f32 v[230:231], v[192:193], v[50:51], v[230:231]
	v_pk_fma_f32 v[226:227], v[194:195], v[54:55], v[226:227]
	v_pk_fma_f32 v[228:229], v[194:195], v[50:51], v[228:229]
	v_fmac_f32_dpp v224, v50, v190 row_shr:1 row_mask:0xf bank_mask:0xf bound_ctrl:1
	v_fmac_f32_dpp v225, v51, v191 row_shr:1 row_mask:0xf bank_mask:0xf bound_ctrl:1
	v_fmac_f32_dpp v230, v62, v194 row_shl:1 row_mask:0xf bank_mask:0xf bound_ctrl:1
	v_fmac_f32_dpp v231, v63, v195 row_shl:1 row_mask:0xf bank_mask:0xf bound_ctrl:1
	v_pk_fma_f32 v[232:233], v[200:201], v[46:47], v[204:205]
	v_pk_fma_f32 v[234:235], v[198:199], v[46:47], v[204:205]
	v_pk_fma_f32 v[236:237], v[198:199], v[42:43], v[204:205]
	v_pk_fma_f32 v[238:239], v[198:199], v[38:39], v[204:205]
	v_pk_fma_f32 v[232:233], v[202:203], v[42:43], v[232:233]
	v_pk_fma_f32 v[234:235], v[200:201], v[42:43], v[234:235]
	v_pk_fma_f32 v[236:237], v[200:201], v[38:39], v[236:237]
	v_pk_fma_f32 v[238:239], v[200:201], v[34:35], v[238:239]
	v_pk_fma_f32 v[234:235], v[202:203], v[38:39], v[234:235]
	v_pk_fma_f32 v[236:237], v[202:203], v[34:35], v[236:237]
	v_fmac_f32_dpp v232, v34, v198 row_shr:1 row_mask:0xf bank_mask:0xf bound_ctrl:1
	v_fmac_f32_dpp v233, v35, v199 row_shr:1 row_mask:0xf bank_mask:0xf bound_ctrl:1
	v_fmac_f32_dpp v238, v46, v202 row_shl:1 row_mask:0xf bank_mask:0xf bound_ctrl:1
	v_fmac_f32_dpp v239, v47, v203 row_shl:1 row_mask:0xf bank_mask:0xf bound_ctrl:1
	v_exp_f32_e64 v240, -v232
	v_exp_f32_e64 v241, -v233
	v_exp_f32_e64 v242, -v234
	v_exp_f32_e64 v243, -v235
	v_exp_f32_e64 v244, -v236
	v_exp_f32_e64 v245, -v237
	v_exp_f32_e64 v246, -v238
	v_exp_f32_e64 v247, -v239
	v_pk_mul_f32 v[224:225], v[224:225], v[232:233]
	v_pk_mul_f32 v[226:227], v[226:227], v[234:235]
	v_pk_mul_f32 v[228:229], v[228:229], v[236:237]
	v_pk_mul_f32 v[230:231], v[230:231], v[238:239]
	v_pk_add_f32 v[240:241], v[240:241], 1.0 op_sel_hi:[1,0]
	v_pk_add_f32 v[242:243], v[242:243], 1.0 op_sel_hi:[1,0]
	v_pk_add_f32 v[244:245], v[244:245], 1.0 op_sel_hi:[1,0]
	v_pk_add_f32 v[246:247], v[246:247], 1.0 op_sel_hi:[1,0]
	v_rcp_f32_e32 v240, v240
	v_rcp_f32_e32 v241, v241
	v_rcp_f32_e32 v242, v242
	v_rcp_f32_e32 v243, v243
	v_rcp_f32_e32 v244, v244
	v_rcp_f32_e32 v245, v245
	v_rcp_f32_e32 v246, v246
	v_rcp_f32_e32 v247, v247
	s_nop 0
	v_pk_mul_f32 v[224:225], v[224:225], v[240:241]
	v_pk_mul_f32 v[226:227], v[226:227], v[242:243]
	v_pk_mul_f32 v[228:229], v[228:229], v[244:245]
	v_pk_mul_f32 v[230:231], v[230:231], v[246:247]
	v_cvt_pk_bf16_f32 v129, v224, v225
	v_cvt_pk_bf16_f32 v133, v226, v227
	v_cvt_pk_bf16_f32 v137, v228, v229
	v_cvt_pk_bf16_f32 v141, v230, v231
	global_load_dwordx4 v[190:193], v172, s[64:65] offset:192
	global_load_dwordx4 v[194:197], v172, s[64:65] offset:208
	global_load_dwordx4 v[198:201], v172, s[64:65] offset:224
	global_load_dwordx4 v[202:205], v172, s[64:65] offset:240
	s_waitcnt vmcnt(4)
	v_pk_mul_f32 v[28:29], v[28:29], v[178:179] op_sel_hi:[1,0]
	v_pk_mul_f32 v[24:25], v[24:25], v[180:181] op_sel_hi:[1,0]
	v_pk_mul_f32 v[20:21], v[20:21], v[182:183] op_sel_hi:[1,0]
	v_pk_mul_f32 v[16:17], v[16:17], v[144:145] op_sel_hi:[1,0]
	v_pk_mul_f32 v[12:13], v[12:13], v[178:179] op_sel_hi:[1,0]
	v_pk_mul_f32 v[8:9], v[8:9], v[180:181] op_sel_hi:[1,0]
	v_pk_mul_f32 v[4:5], v[4:5], v[182:183] op_sel_hi:[1,0]
	v_pk_mul_f32 v[0:1], v[0:1], v[144:145] op_sel_hi:[1,0]
	v_pk_fma_f32 v[224:225], v[208:209], v[28:29], v[212:213]
	v_pk_fma_f32 v[226:227], v[206:207], v[28:29], v[212:213]
	v_pk_fma_f32 v[228:229], v[206:207], v[24:25], v[212:213]
	v_pk_fma_f32 v[230:231], v[206:207], v[20:21], v[212:213]
	v_pk_fma_f32 v[224:225], v[210:211], v[24:25], v[224:225]
	v_pk_fma_f32 v[226:227], v[208:209], v[24:25], v[226:227]
	v_pk_fma_f32 v[228:229], v[208:209], v[20:21], v[228:229]
	v_pk_fma_f32 v[230:231], v[208:209], v[16:17], v[230:231]
	v_pk_fma_f32 v[226:227], v[210:211], v[20:21], v[226:227]
	v_pk_fma_f32 v[228:229], v[210:211], v[16:17], v[228:229]
	v_fmac_f32_dpp v224, v16, v206 row_shr:1 row_mask:0xf bank_mask:0xf bound_ctrl:1
	v_fmac_f32_dpp v225, v17, v207 row_shr:1 row_mask:0xf bank_mask:0xf bound_ctrl:1
	v_fmac_f32_dpp v230, v28, v210 row_shl:1 row_mask:0xf bank_mask:0xf bound_ctrl:1
	v_fmac_f32_dpp v231, v29, v211 row_shl:1 row_mask:0xf bank_mask:0xf bound_ctrl:1
	v_pk_fma_f32 v[232:233], v[216:217], v[12:13], v[220:221]
	v_pk_fma_f32 v[234:235], v[214:215], v[12:13], v[220:221]
	v_pk_fma_f32 v[236:237], v[214:215], v[8:9], v[220:221]
	v_pk_fma_f32 v[238:239], v[214:215], v[4:5], v[220:221]
	v_pk_fma_f32 v[232:233], v[218:219], v[8:9], v[232:233]
	v_pk_fma_f32 v[234:235], v[216:217], v[8:9], v[234:235]
	v_pk_fma_f32 v[236:237], v[216:217], v[4:5], v[236:237]
	v_pk_fma_f32 v[238:239], v[216:217], v[0:1], v[238:239]
; __device__ __forceinline__ unsigned cvtpk(float lo, float hi) { f32x2 v = {lo, hi}; bf16x2_t b = __builtin_convertvector(v, bf16x2_t); return __builtin_bit_cast(unsigned, b); }
;     __device__ __forceinline__ void operator()(const f32x4 (&acc)[2][2][4][2], const Unit& u, int wr, int wc, int fr, int fq) const {
;     ...
;                     {
;                         f32x2 rv[4], lv[4];
; #pragma unroll
;                         for (int m = 0; m < 4; ++m) { uv[m] = uv[m] * rs[m]; rv[m] = (f32x2){dpp_ror1(uv[m][0]), dpp_ror1(uv[m][1])}; lv[m] = (f32x2){dpp_ror15(uv[m][0]), dpp_ror15(uv[m][1])}; }
; #pragma unroll
;                         for (int m = 0; m < 4; ++m) { const f32x2 pv_ = (m > 0 && f0) ? rv[m > 0 ? m - 1 : 0] : rv[m], nv_ = (m < 3 && f15) ? lv[m < 3 ? m + 1 : 3] : lv[m];
;                             cv[m] = bv + wv0 * pv_ + wv1 * uv[m] + wv2 * nv_; }
;                     }
;                     asm volatile("" : "+v"(cv[0]), "+v"(cv[1]), "+v"(cv[2]), "+v"(cv[3]));
;                     {
;                         f32x2 rg[4], lg[4];
; #pragma unroll
;                         for (int m = 0; m < 4; ++m) { ug[m] = ug[m] * rs[m]; rg[m] = (f32x2){dpp_ror1(ug[m][0]), dpp_ror1(ug[m][1])}; lg[m] = (f32x2){dpp_ror15(ug[m][0]), dpp_ror15(ug[m][1])}; }
; #pragma unroll
;                         for (int m = 0; m < 4; ++m) { const f32x2 pg_ = (m > 0 && f0) ? rg[m > 0 ? m - 1 : 0] : rg[m], ng_ = (m < 3 && f15) ? lg[m < 3 ? m + 1 : 3] : lg[m];
;                             const f32x2 cgt = bg + wg0 * pg_ + wg1 * ug[m] + wg2 * ng_;
;                             const f32x2 e = cgt * (-LOG2E);
;                             const f32x2 d = (f32x2){__builtin_amdgcn_exp2f(e[0]), __builtin_amdgcn_exp2f(e[1])} + 1.f;
;                             const f32x2 sg = {__builtin_amdgcn_rcpf(d[0]), __builtin_amdgcn_rcpf(d[1])};
;                             const f32x2 ov = cv[m] * cgt * sg;
;                             outw[m][n][jp] = cvtpk(ov[0], ov[1]); }
;     ...
; #pragma unroll
;             for (int m = 0; m < 4; ++m) { const int i = 16 * m + fr, t = tbase + i;
;                 if (i >= 1 && i <= 62 && t < slen) { u32x4 w; w.x = outw[m][0][0]; w.y = outw[m][0][1]; w.z = outw[m][1][0]; w.w = outw[m][1][1];
;                     *(u32x4*)(Gout + (size_t)(seqbase + t) * DFF + 128 * u.pn + 32 * wc + 8 * fq) = w; } }
	v_pk_fma_f32 v[234:235], v[218:219], v[4:5], v[234:235]
	v_pk_fma_f32 v[236:237], v[218:219], v[0:1], v[236:237]
	v_fmac_f32_dpp v232, v0, v214 row_shr:1 row_mask:0xf bank_mask:0xf bound_ctrl:1
	v_fmac_f32_dpp v233, v1, v215 row_shr:1 row_mask:0xf bank_mask:0xf bound_ctrl:1
	v_fmac_f32_dpp v238, v12, v218 row_shl:1 row_mask:0xf bank_mask:0xf bound_ctrl:1
	v_fmac_f32_dpp v239, v13, v219 row_shl:1 row_mask:0xf bank_mask:0xf bound_ctrl:1
	v_exp_f32_e64 v240, -v232
	v_exp_f32_e64 v241, -v233
	v_exp_f32_e64 v242, -v234
	v_exp_f32_e64 v243, -v235
	v_exp_f32_e64 v244, -v236
	v_exp_f32_e64 v245, -v237
	v_exp_f32_e64 v246, -v238
	v_exp_f32_e64 v247, -v239
	v_pk_mul_f32 v[224:225], v[224:225], v[232:233]
	v_pk_mul_f32 v[226:227], v[226:227], v[234:235]
	v_pk_mul_f32 v[228:229], v[228:229], v[236:237]
	v_pk_mul_f32 v[230:231], v[230:231], v[238:239]
	v_pk_add_f32 v[240:241], v[240:241], 1.0 op_sel_hi:[1,0]
	v_pk_add_f32 v[242:243], v[242:243], 1.0 op_sel_hi:[1,0]
	v_pk_add_f32 v[244:245], v[244:245], 1.0 op_sel_hi:[1,0]
	v_pk_add_f32 v[246:247], v[246:247], 1.0 op_sel_hi:[1,0]
	v_rcp_f32_e32 v240, v240
	v_rcp_f32_e32 v241, v241
	v_rcp_f32_e32 v242, v242
	v_rcp_f32_e32 v243, v243
	v_rcp_f32_e32 v244, v244
	v_rcp_f32_e32 v245, v245
	v_rcp_f32_e32 v246, v246
	v_rcp_f32_e32 v247, v247
	s_nop 0
	v_pk_mul_f32 v[224:225], v[224:225], v[240:241]
	v_pk_mul_f32 v[226:227], v[226:227], v[242:243]
	v_pk_mul_f32 v[228:229], v[228:229], v[244:245]
	v_pk_mul_f32 v[230:231], v[230:231], v[246:247]
	v_cvt_pk_bf16_f32 v130, v224, v225
	v_cvt_pk_bf16_f32 v134, v226, v227
	v_cvt_pk_bf16_f32 v138, v228, v229
	v_cvt_pk_bf16_f32 v142, v230, v231
	s_waitcnt vmcnt(0)
	v_pk_mul_f32 v[30:31], v[30:31], v[178:179] op_sel_hi:[1,0]
	v_pk_mul_f32 v[26:27], v[26:27], v[180:181] op_sel_hi:[1,0]
	v_pk_mul_f32 v[22:23], v[22:23], v[182:183] op_sel_hi:[1,0]
	v_pk_mul_f32 v[18:19], v[18:19], v[144:145] op_sel_hi:[1,0]
	v_pk_mul_f32 v[14:15], v[14:15], v[178:179] op_sel_hi:[1,0]
	v_pk_mul_f32 v[10:11], v[10:11], v[180:181] op_sel_hi:[1,0]
	v_pk_mul_f32 v[6:7], v[6:7], v[182:183] op_sel_hi:[1,0]
	v_pk_mul_f32 v[2:3], v[2:3], v[144:145] op_sel_hi:[1,0]
	v_pk_fma_f32 v[224:225], v[192:193], v[30:31], v[196:197]
	v_pk_fma_f32 v[226:227], v[190:191], v[30:31], v[196:197]
	v_pk_fma_f32 v[228:229], v[190:191], v[26:27], v[196:197]
	v_pk_fma_f32 v[230:231], v[190:191], v[22:23], v[196:197]
	v_pk_fma_f32 v[224:225], v[194:195], v[26:27], v[224:225]
	v_pk_fma_f32 v[226:227], v[192:193], v[26:27], v[226:227]
	v_pk_fma_f32 v[228:229], v[192:193], v[22:23], v[228:229]
	v_pk_fma_f32 v[230:231], v[192:193], v[18:19], v[230:231]
	v_pk_fma_f32 v[226:227], v[194:195], v[22:23], v[226:227]
	v_pk_fma_f32 v[228:229], v[194:195], v[18:19], v[228:229]
	v_fmac_f32_dpp v224, v18, v190 row_shr:1 row_mask:0xf bank_mask:0xf bound_ctrl:1
	v_fmac_f32_dpp v225, v19, v191 row_shr:1 row_mask:0xf bank_mask:0xf bound_ctrl:1
	v_fmac_f32_dpp v230, v30, v194 row_shl:1 row_mask:0xf bank_mask:0xf bound_ctrl:1
	v_fmac_f32_dpp v231, v31, v195 row_shl:1 row_mask:0xf bank_mask:0xf bound_ctrl:1
	v_pk_fma_f32 v[232:233], v[200:201], v[14:15], v[204:205]
	v_pk_fma_f32 v[234:235], v[198:199], v[14:15], v[204:205]
	v_pk_fma_f32 v[236:237], v[198:199], v[10:11], v[204:205]
	v_pk_fma_f32 v[238:239], v[198:199], v[6:7], v[204:205]
	v_pk_fma_f32 v[232:233], v[202:203], v[10:11], v[232:233]
	v_pk_fma_f32 v[234:235], v[200:201], v[10:11], v[234:235]
	v_pk_fma_f32 v[236:237], v[200:201], v[6:7], v[236:237]
	v_pk_fma_f32 v[238:239], v[200:201], v[2:3], v[238:239]
	v_pk_fma_f32 v[234:235], v[202:203], v[6:7], v[234:235]
	v_pk_fma_f32 v[236:237], v[202:203], v[2:3], v[236:237]
	v_fmac_f32_dpp v232, v2, v198 row_shr:1 row_mask:0xf bank_mask:0xf bound_ctrl:1
	v_fmac_f32_dpp v233, v3, v199 row_shr:1 row_mask:0xf bank_mask:0xf bound_ctrl:1
	v_fmac_f32_dpp v238, v14, v202 row_shl:1 row_mask:0xf bank_mask:0xf bound_ctrl:1
	v_fmac_f32_dpp v239, v15, v203 row_shl:1 row_mask:0xf bank_mask:0xf bound_ctrl:1
	v_exp_f32_e64 v240, -v232
	v_exp_f32_e64 v241, -v233
	v_exp_f32_e64 v242, -v234
	v_exp_f32_e64 v243, -v235
	v_exp_f32_e64 v244, -v236
	v_exp_f32_e64 v245, -v237
	v_exp_f32_e64 v246, -v238
	v_exp_f32_e64 v247, -v239
	v_pk_mul_f32 v[224:225], v[224:225], v[232:233]
	v_pk_mul_f32 v[226:227], v[226:227], v[234:235]
	v_pk_mul_f32 v[228:229], v[228:229], v[236:237]
	v_pk_mul_f32 v[230:231], v[230:231], v[238:239]
	v_pk_add_f32 v[240:241], v[240:241], 1.0 op_sel_hi:[1,0]
	v_pk_add_f32 v[242:243], v[242:243], 1.0 op_sel_hi:[1,0]
	v_pk_add_f32 v[244:245], v[244:245], 1.0 op_sel_hi:[1,0]
	v_pk_add_f32 v[246:247], v[246:247], 1.0 op_sel_hi:[1,0]
	v_rcp_f32_e32 v240, v240
	v_rcp_f32_e32 v241, v241
	v_rcp_f32_e32 v242, v242
	v_rcp_f32_e32 v243, v243
	v_rcp_f32_e32 v244, v244
	v_rcp_f32_e32 v245, v245
	v_rcp_f32_e32 v246, v246
	v_rcp_f32_e32 v247, v247
	s_nop 0
	v_pk_mul_f32 v[224:225], v[224:225], v[240:241]
	v_pk_mul_f32 v[226:227], v[226:227], v[242:243]
	v_pk_mul_f32 v[228:229], v[228:229], v[244:245]
	v_pk_mul_f32 v[230:231], v[230:231], v[246:247]
	v_cvt_pk_bf16_f32 v131, v224, v225
	v_cvt_pk_bf16_f32 v135, v226, v227
	v_cvt_pk_bf16_f32 v139, v228, v229
	v_cvt_pk_bf16_f32 v143, v230, v231
	s_sub_i32 s51, s91, s89
	s_sub_i32 s66, s51, 4
	s_max_i32 s66, s66, 0
	v_add_u32_e32 v176, -4, v164
	v_cmp_gt_u32_e32 vcc, s66, v176
	v_add_u32_e32 v176, 0, v174
	v_add_u32_e32 v176, s88, v176
	v_mad_u32_u24 v248, v176, s54, v165
	s_mov_b64 exec, vcc
	global_store_dwordx4 v248, v[128:131], s[86:87]
	s_mov_b64 exec, -1
	s_sub_i32 s66, s51, 1
	s_max_i32 s66, s66, 0
	v_cmp_gt_u32_e32 vcc, s66, v164
	v_add_u32_e32 v176, 1, v174
	v_add_u32_e32 v176, s88, v176
	v_mad_u32_u24 v249, v176, s54, v165
	s_mov_b64 exec, vcc
	global_store_dwordx4 v249, v[132:135], s[86:87]
	s_mov_b64 exec, -1
	s_sub_i32 s66, s51, 2
	s_max_i32 s66, s66, 0
	v_cmp_gt_u32_e32 vcc, s66, v164
	v_add_u32_e32 v176, 2, v174
	v_add_u32_e32 v176, s88, v176
	v_mad_u32_u24 v250, v176, s54, v165
	s_mov_b64 exec, vcc
	global_store_dwordx4 v250, v[136:139], s[86:87]
	s_mov_b64 exec, -1
	s_sub_i32 s66, s51, 3
	s_min_i32 s66, s66, 60
	s_max_i32 s66, s66, 0
	v_cmp_gt_u32_e32 vcc, s66, v164
	v_add_u32_e32 v176, 3, v174
	v_add_u32_e32 v176, s88, v176
	v_mad_u32_u24 v251, v176, s54, v165
	s_mov_b64 exec, vcc
	global_store_dwordx4 v251, v[140:143], s[86:87]
	s_mov_b64 exec, -1
	s_mov_b64 s[2:3], exec
